# chain the rotation offsets of the five small GEMMs so their partial rounds land on different workgroups
# baseline (speedup 1.0000x reference)
; DI void run_phase(PP p, int ph, LAS unsigned char* lds) {
;     ...
;     case 3: if (!(PHMASK & (4<<3))) break; {
;         if (SUBM & 1) { pg8::EpiLora E; E.DEC = (float*)(ws + X_DEC); E.AA = (u16*)(ws + X_AA); E.G = (u16*)(ws + X_G); E.w0 = p->in[I_W0] + l * 1024; E.a0 = p->in[I_A0] + l * 1024;
;           E.pn_off = 0; run_gemm(lds, (const u16*)(ws + OFF_ALORA), (const u16*)(sm + SZ_UQ + SZ_UKV), NTOK, 2048, 384, E, 0, 640, 640);
;           E.pn_off = 8; run_gemm(lds, (const u16*)(ws + OFF_ALORA) + 384, (const u16*)(sm + SZ_UQ + SZ_UKV) + (size_t)2048 * 640 + 384, NTOK, 512, 256, E, 64, 640, 640); }
;         if (SUBM & 2) { pg8::EpiKV E; E.K = (u16*)(ws + X_K); E.VT = (u16*)(ws + X_VT); E.row_off = 0;
;           run_gemm(lds, (const u16*)(ws + OFF_AKV), (const u16*)(sm + SZ_UQ), NTOK, 1024, 256, E, 208); }
;         if (SUBM & 4) { pg8::EpiQ E; E.Q = (u16*)(ws + X_Q); E.rope = (const float*)(ws + OFF_ROPE); E.row_off = row_lo; E.qscale = 0.07216878364870322f * 1.4426950408889634f;
;           run_gemm(lds, (const u16*)(ws + OFF_AQ) + (size_t)row_lo * 384, (const u16*)sm, Mrows, 768, 384, E, 240); }
;         if (SUBM & 8) { pg8::EpiBf16<0> E; E.O = ACT + 1024; E.ldc = D; E.row_off = row_lo;
;           run_gemm(lds, (const u16*)(ws + OFF_APOOL) + (size_t)row_lo * 512, (const u16*)(sm + SZ_UQ + SZ_UKV + SZ_LORA), Mrows, 512, 512, E, 200); }
.LBB0_6:
	s_lshl_b32 s20, s64, 3
	s_lshl_b32 s78, s2, 3
	s_add_i32 s18, s20, 0x3fff
	s_cmpk_lt_i32 s2, 0x300
	s_cselect_b64 s[0:1], -1, 0
	v_writelane_b32 v252, s0, 4
	s_mov_b32 s71, 0
	s_mov_b32 s70, s64
	v_writelane_b32 v252, s1, 5
	s_lshl_b32 s0, s2, 11
	s_and_b32 s19, s0, 0x1800
	s_lshr_b32 s0, s64, 2
	v_writelane_b32 v252, s0, 6
	s_lshr_b32 s0, s2, 2
	v_writelane_b32 v252, s0, 7
	s_bfe_u32 s0, s2, 0x30002
	v_writelane_b32 v252, s0, 8
	s_lshr_b32 s0, s2, 5
	v_writelane_b32 v252, s0, 9
	s_ashr_i32 s0, s64, 31
	v_writelane_b32 v252, s0, 10
	s_lshl_b64 s[0:1], s[70:71], 3
	v_writelane_b32 v252, s0, 11
	s_mov_b32 s3, s71
	s_add_i32 s17, s2, 0x48
	s_add_i32 s33, s2, 0x68
	s_add_i32 s25, s2, 0x88
	s_add_i32 s16, s2, 0xa8
	s_add_i32 s15, s2, 56
	s_add_i32 s14, s2, 0xcc
	s_add_i32 s12, s2, 48
	s_add_i32 s11, s2, 0xd4
	s_add_i32 s10, s2, 0x60
	v_writelane_b32 v252, s1, 12
	s_lshl_b64 s[0:1], s[2:3], 3
	v_writelane_b32 v252, s0, 13
	s_cmpk_lt_i32 s2, 0x100
	s_brev_b32 s84, 60
	v_writelane_b32 v252, s1, 14
	s_cselect_b64 s[0:1], -1, 0
	v_writelane_b32 v252, s0, 15
	s_add_i32 s9, s2, 0xc0
	s_add_i32 s8, s2, 16
	v_writelane_b32 v252, s1, 16
	s_lshl_b64 s[0:1], s[2:3], 9
	v_writelane_b32 v252, s0, 17
	s_cmp_gt_i32 s64, -1
	v_mov_b32_e32 v97, 0
	v_writelane_b32 v252, s1, 18
	s_cselect_b64 s[0:1], -1, 0
	s_add_i32 s3, s20, 0x47ff
	s_cmp_lg_u32 s82, 0
	s_cselect_b64 s[22:23], -1, 0
	v_writelane_b32 v252, s22, 19
	s_cmp_lg_u32 s82, 2
	v_mov_b32_e32 v166, 0x358637bd
	v_writelane_b32 v252, s23, 20
	s_cselect_b64 s[22:23], -1, 0
	v_writelane_b32 v252, s22, 21
	v_mov_b32_e32 v183, 0x3a27c5ac
	s_mov_b32 s85, 0x3b2aaaab
	v_writelane_b32 v252, s23, 22
	s_add_u32 s22, s4, 0x960200
	s_addc_u32 s23, s5, 0
	v_writelane_b32 v252, s22, 23
	v_mov_b32_e32 v184, 1
	v_mov_b32_e32 v186, 0x90000
	v_writelane_b32 v252, s23, 24
	s_add_u32 s22, s4, 0x960400
	s_addc_u32 s23, s5, 0
	v_writelane_b32 v252, s22, 25
	v_mov_b32_e32 v187, 0x41b17218
	v_mov_b32_e32 v188, 0x7f8
	v_writelane_b32 v252, s23, 26
	s_add_u32 s22, s4, 0x960500
	s_addc_u32 s23, s5, 0
	v_writelane_b32 v252, s22, 27
	v_mov_b32_e32 v189, 0xf8
	v_mov_b32_e32 v190, 0x800
	v_writelane_b32 v252, s23, 28
	s_add_u32 s22, s4, 0x960600
	s_addc_u32 s23, s5, 0
	v_writelane_b32 v252, s22, 29
	v_mov_b32_e32 v191, 0x100
	v_mov_b32_e32 v192, 0x7ff
	v_writelane_b32 v252, s23, 30
	s_add_u32 s22, s4, 0x960700
	s_addc_u32 s23, s5, 0
	v_writelane_b32 v252, s22, 31
	v_mov_b32_e32 v193, 0xff
	v_mov_b32_e32 v194, 0x7fc
	v_writelane_b32 v252, s23, 32
	s_add_u32 s22, s4, 0x960800
	s_addc_u32 s23, s5, 0
	v_writelane_b32 v252, s22, 33
	v_bfrev_b32_e32 v195, 0.5
	s_movk_i32 s70, 0x300
	v_writelane_b32 v252, s23, 34
	s_add_u32 s22, s4, 0x960900
	s_addc_u32 s23, s5, 0
	v_writelane_b32 v252, s22, 35
	s_mov_b32 s79, 0x800000
	s_mov_b32 s72, 0xc000
	v_writelane_b32 v252, s23, 36
	s_add_u32 s22, s4, 0x960a00
	s_addc_u32 s23, s5, 0
	v_writelane_b32 v252, s22, 37
	s_movk_i32 s66, 0x500
	s_movk_i32 s67, 0x104
	v_writelane_b32 v252, s23, 38
	s_add_u32 s22, s4, 0x960b00
	s_addc_u32 s23, s5, 0
	v_writelane_b32 v252, s22, 39
	s_movk_i32 s62, 0xc00
	s_mov_b32 s63, 0xfffb8000
	v_writelane_b32 v252, s23, 40
	s_add_u32 s22, s4, 0x960c00
	s_addc_u32 s23, s5, 0
	v_writelane_b32 v252, s22, 41
	s_movk_i32 s40, 0x5f
	s_mov_b64 s[28:29], 0x80
	v_writelane_b32 v252, s23, 42
	s_add_u32 s22, s4, 0x960d00
	s_addc_u32 s23, s5, 0
	v_writelane_b32 v252, s22, 43
	s_nop 1
	v_writelane_b32 v252, s23, 44
	s_add_u32 s22, s4, 0x960e00
	s_addc_u32 s23, s5, 0
	v_writelane_b32 v252, s22, 45
	s_nop 1
	v_writelane_b32 v252, s23, 46
	s_add_u32 s22, s4, 0x960f00
	s_addc_u32 s23, s5, 0
	v_writelane_b32 v252, s22, 47
	s_nop 1
	v_writelane_b32 v252, s23, 48
	s_add_u32 s22, s4, 0x961000
	s_addc_u32 s23, s5, 0
	v_writelane_b32 v252, s22, 49
	s_nop 1
	v_writelane_b32 v252, s23, 50
	s_add_u32 s22, s4, 0x961100
	s_addc_u32 s23, s5, 0
	v_writelane_b32 v252, s22, 51
	s_nop 1
	v_writelane_b32 v252, s23, 52
	s_add_u32 s22, s4, 0x961200
	s_addc_u32 s23, s5, 0
	v_writelane_b32 v252, s22, 53
	s_nop 1
	v_writelane_b32 v252, s23, 54
	s_add_u32 s22, s4, 0x961300
	s_addc_u32 s23, s5, 0
	v_writelane_b32 v252, s22, 55
	s_cmp_eq_u32 s13, 15
	s_nop 0
	v_writelane_b32 v252, s23, 56
	s_cselect_b64 s[22:23], -1, 0
	v_writelane_b32 v252, s22, 57
	s_cmp_eq_u32 s13, 14
	s_nop 0
	v_writelane_b32 v252, s23, 58
	s_cselect_b64 s[22:23], -1, 0
	v_writelane_b32 v252, s22, 59
	s_cmp_eq_u32 s13, 13
	s_nop 0
	v_writelane_b32 v252, s23, 60
	s_cselect_b64 s[22:23], -1, 0
	v_writelane_b32 v252, s22, 61
	s_cmp_eq_u32 s13, 12
	s_nop 0
	v_writelane_b32 v252, s23, 62
	s_cselect_b64 s[22:23], -1, 0
	v_writelane_b32 v252, s22, 63
	s_cmp_eq_u32 s13, 11
	v_readlane_b32 s82, v252, 0
	v_writelane_b32 v253, s23, 0
	s_cselect_b64 s[22:23], -1, 0
	v_writelane_b32 v253, s22, 1
	s_cmp_eq_u32 s13, 10
	v_readlane_b32 s83, v252, 1
	v_writelane_b32 v253, s23, 2
	s_cselect_b64 s[22:23], -1, 0
	v_writelane_b32 v253, s22, 3
	s_cmp_eq_u32 s13, 9
	s_nop 0
	v_writelane_b32 v253, s23, 4
	s_cselect_b64 s[22:23], -1, 0
	v_writelane_b32 v253, s22, 5
	s_cmp_eq_u32 s13, 8
	s_nop 0
	v_writelane_b32 v253, s23, 6
	s_cselect_b64 s[22:23], -1, 0
	v_writelane_b32 v253, s22, 7
	s_cmp_eq_u32 s13, 7
	s_nop 0
	v_writelane_b32 v253, s23, 8
	s_cselect_b64 s[22:23], -1, 0
	v_writelane_b32 v253, s22, 9
	s_cmp_eq_u32 s13, 6
	s_nop 0
	v_writelane_b32 v253, s23, 10
	s_cselect_b64 s[22:23], -1, 0
	v_writelane_b32 v253, s22, 11
	s_cmp_eq_u32 s13, 5
	s_nop 0
	v_writelane_b32 v253, s23, 12
	s_cselect_b64 s[22:23], -1, 0
	v_writelane_b32 v253, s22, 13
	s_cmp_eq_u32 s13, 4
	s_nop 0
	v_writelane_b32 v253, s23, 14
	s_cselect_b64 s[22:23], -1, 0
	v_writelane_b32 v253, s22, 15
; #define LAS __attribute__((address_space(3)))
; DI int tid_() { int t = threadIdx.x; asm volatile("" : "+v"(t)); return t; }
; __device__ __forceinline__ unsigned xb_ld(unsigned* p)              { return __hip_atomic_load(p, __ATOMIC_RELAXED, __HIP_MEMORY_SCOPE_AGENT); }
;     ...
;     pg8::StaticOrder S; S.init(M, N, (int)gridDim.x, (int)((blockIdx.x + (unsigned)rot) % gridDim.x));
;     pg8::gemm_phase<Epi, pg8::StaticOrder>(lds, g, S, E);
; }
;     LAS float* T = (LAS float*)lds;
;     const int tid = tid_();
;     const int nkt = (K + 63) >> 6, nng = (N + 255) >> 8, nitem = nkt * nng;
;     const int t_step = nwk ? nwk : (int)gridDim.x; const int t_first = nwk ? wk : (int)((blockIdx.x + (unsigned)rot) % gridDim.x);
; __device__ __forceinline__ void xcd_barrier_complete(unsigned* bar, unsigned x, unsigned& nloc, unsigned& nx) {
;     ...
;         for (unsigned j = 0; j < 16; ++j) { const unsigned c = xb_ld(&bar[XB_XCNT(j)]); sum += c; cnt += (c > 0u) ? 1u : 0u; mine = (j == x) ? c : mine; }
	s_cmp_eq_u32 s13, 3
	s_nop 0
	v_writelane_b32 v253, s23, 16
	s_cselect_b64 s[22:23], -1, 0
	v_writelane_b32 v253, s22, 17
	s_cmp_eq_u32 s13, 2
	s_nop 0
	v_writelane_b32 v253, s23, 18
	s_cselect_b64 s[22:23], -1, 0
	v_writelane_b32 v253, s22, 19
	s_cmp_eq_u32 s13, 1
	s_nop 0
	v_writelane_b32 v253, s23, 20
	s_cselect_b64 s[22:23], -1, 0
	v_writelane_b32 v253, s22, 21
	s_cmp_eq_u32 s13, 0
	s_nop 0
	v_writelane_b32 v253, s23, 22
	s_cselect_b64 s[22:23], -1, 0
	s_lshl_b32 s13, s13, 8
	s_add_u32 s6, s6, s13
	v_writelane_b32 v253, s22, 23
	s_addc_u32 s7, s7, 0
	s_nop 0
	v_writelane_b32 v253, s23, 24
	s_add_u32 s22, s6, 0x1400
	s_addc_u32 s23, s7, 0
	v_writelane_b32 v253, s22, 25
	s_add_u32 s6, s6, 0x2400
	s_addc_u32 s7, s7, 0
	v_writelane_b32 v253, s23, 26
	v_writelane_b32 v253, s6, 27
	s_nop 1
	v_writelane_b32 v253, s7, 28
	s_add_u32 s6, s4, 0x963400
	s_addc_u32 s7, s5, 0
	s_add_u32 s4, s4, 0x963500
	s_addc_u32 s5, s5, 0
	s_abs_i32 s21, s20
	v_cvt_f32_u32_e32 v1, s21
	v_writelane_b32 v253, s6, 29
	v_rcp_iflag_f32_e32 v1, v1
	s_nop 0
	v_writelane_b32 v253, s7, 30
	v_writelane_b32 v253, s4, 31
	v_mul_f32_e32 v1, 0x4f7ffffe, v1
	v_cvt_u32_f32_e32 v1, v1
	v_writelane_b32 v253, s5, 32
	s_sub_i32 s4, 0, s21
	v_readfirstlane_b32 s5, v1
	s_mul_i32 s4, s4, s5
	s_mul_hi_u32 s4, s5, s4
	s_add_i32 s22, s5, s4
	s_sub_i32 s4, 0xffffc001, s20
	s_max_i32 s4, s18, s4
	s_mul_hi_u32 s5, s4, s22
	s_mul_i32 s6, s5, s21
	v_cvt_f32_u32_e32 v1, s64
	s_sub_i32 s4, s4, s6
	s_ashr_i32 s6, s18, 31
	s_bfe_i32 s18, s64, 0x1001c
	s_xor_b32 s6, s6, s18
	s_add_i32 s7, s5, 1
	s_sub_i32 s13, s4, s21
	s_cmp_ge_u32 s4, s21
	s_cselect_b32 s5, s7, s5
	v_rcp_iflag_f32_e32 v1, v1
	s_cselect_b32 s4, s13, s4
	s_add_i32 s7, s5, 1
	s_cmp_ge_u32 s4, s21
	s_cselect_b32 s4, s7, s5
	s_xor_b32 s4, s4, s6
	v_mul_f32_e32 v1, 0x4f7ffffe, v1
	s_sub_i32 s4, s4, s6
	v_cvt_u32_f32_e32 v1, v1
	s_cmp_gt_i32 s4, 0
	v_writelane_b32 v253, s4, 33
	s_cselect_b64 s[4:5], -1, 0
	v_writelane_b32 v253, s4, 34
	s_nop 1
	v_writelane_b32 v253, s5, 35
	s_sub_i32 s4, 0, s64
	v_readfirstlane_b32 s5, v1
	s_mul_i32 s4, s4, s5
	s_mul_hi_u32 s4, s5, s4
	s_add_i32 s13, s5, s4
	s_mul_hi_u32 s4, s2, s13
	s_mul_i32 s4, s4, s64
	s_sub_i32 s4, s2, s4
	s_sub_i32 s5, s4, s64
	s_cmp_ge_u32 s4, s64
	s_cselect_b32 s4, s5, s4
	s_sub_i32 s5, s4, s64
	s_cmp_ge_u32 s4, s64
	s_cselect_b32 s23, s5, s4
	s_mul_hi_u32 s4, s17, s13
	s_cmp_lt_i32 s23, 18
	s_mul_i32 s4, s4, s64
	s_cselect_b64 s[6:7], -1, 0
	s_sub_i32 s4, s17, s4
	s_sub_i32 s5, s4, s64
	s_cmp_ge_u32 s4, s64
	s_cselect_b32 s4, s5, s4
	s_sub_i32 s5, s4, s64
	s_cmp_ge_u32 s4, s64
	s_cselect_b32 s24, s5, s4
	s_mul_hi_u32 s4, s16, s13
	v_writelane_b32 v253, s6, 36
	s_cmp_lt_i32 s24, 8
	s_mul_i32 s4, s4, s64
	v_writelane_b32 v253, s7, 37
	s_cselect_b64 s[6:7], -1, 0
	s_sub_i32 s4, s16, s4
	s_sub_i32 s5, s4, s64
	s_cmp_ge_u32 s4, s64
	s_cselect_b32 s4, s5, s4
	s_sub_i32 s5, s4, s64
	s_cmp_ge_u32 s4, s64
	s_cselect_b32 s16, s5, s4
	s_mul_hi_u32 s4, s15, s13
	v_writelane_b32 v253, s6, 38
	s_cmp_lt_i32 s16, 8
	s_mul_i32 s4, s4, s64
	v_writelane_b32 v253, s7, 39
	s_cselect_b64 s[6:7], -1, 0
	s_sub_i32 s4, s15, s4
	s_sub_i32 s5, s4, s64
	s_cmp_ge_u32 s4, s64
	s_cselect_b32 s4, s5, s4
	s_sub_i32 s5, s4, s64
	s_cmp_ge_u32 s4, s64
	s_cselect_b32 s15, s5, s4
	s_mul_hi_u32 s4, s14, s13
	v_writelane_b32 v253, s6, 40
	s_cmp_lt_i32 s15, 2
	s_mul_i32 s4, s4, s64
	v_writelane_b32 v253, s7, 41
	s_cselect_b64 s[6:7], -1, 0
	s_sub_i32 s4, s14, s4
	s_sub_i32 s5, s4, s64
	s_cmp_ge_u32 s4, s64
	s_cselect_b32 s4, s5, s4
	s_sub_i32 s5, s4, s64
	s_cmp_ge_u32 s4, s64
	s_cselect_b32 s14, s5, s4
	s_mul_hi_u32 s4, s12, s13
	v_writelane_b32 v253, s6, 42
	s_cmp_lt_i32 s14, 2
	s_mul_i32 s4, s4, s64
	v_writelane_b32 v253, s7, 43
	s_cselect_b64 s[6:7], -1, 0
	s_sub_i32 s4, s12, s4
	s_sub_i32 s5, s4, s64
	s_cmp_ge_u32 s4, s64
	s_cselect_b32 s4, s5, s4
	s_sub_i32 s5, s4, s64
	s_cmp_ge_u32 s4, s64
	s_cselect_b32 s12, s5, s4
	s_mul_hi_u32 s4, s11, s13
	v_writelane_b32 v253, s6, 44
	s_cmp_lt_i32 s12, 2
	s_mul_i32 s4, s4, s64
	v_writelane_b32 v253, s7, 45
	s_cselect_b64 s[6:7], -1, 0
	s_sub_i32 s4, s11, s4
	s_sub_i32 s5, s4, s64
	s_cmp_ge_u32 s4, s64
	s_cselect_b32 s4, s5, s4
	s_sub_i32 s5, s4, s64
	s_cmp_ge_u32 s4, s64
	s_cselect_b32 s11, s5, s4
	v_writelane_b32 v253, s6, 46
	s_cmp_lt_i32 s11, 2
	s_cselect_b64 s[4:5], -1, 0
	v_writelane_b32 v253, s7, 47
	v_writelane_b32 v253, s4, 48
	s_cmpk_lt_i32 s23, 0x260
	s_cselect_b64 s[6:7], -1, 0
	v_writelane_b32 v253, s5, 49
	v_writelane_b32 v253, s6, 50
	s_ashr_i32 s5, s23, 31
	s_mul_hi_u32 s4, s10, s13
	v_writelane_b32 v253, s7, 51
	v_writelane_b32 v253, s5, 52
	s_lshr_b32 s5, s5, 29
	s_add_i32 s5, s23, s5
	s_mul_i32 s4, s4, s64
	s_ashr_i32 s6, s5, 3
	s_and_b32 s5, s5, -8
	s_sub_i32 s4, s10, s4
	v_writelane_b32 v253, s6, 53
	s_sub_i32 s5, s23, s5
	v_writelane_b32 v253, s5, 54
	s_sub_i32 s5, s4, s64
	s_cmp_ge_u32 s4, s64
	s_cselect_b32 s4, s5, s4
	s_sub_i32 s5, s4, s64
	s_cmp_ge_u32 s4, s64
	s_cselect_b32 s10, s5, s4
	s_mul_hi_u32 s4, s9, s13
	s_cmpk_lt_i32 s10, 0x100
	s_mul_i32 s4, s4, s64
	s_cselect_b64 s[6:7], -1, 0
	s_sub_i32 s4, s9, s4
	s_sub_i32 s5, s4, s64
	s_cmp_ge_u32 s4, s64
	s_cselect_b32 s4, s5, s4
	s_sub_i32 s5, s4, s64
	v_writelane_b32 v253, s6, 55
	s_cmp_ge_u32 s4, s64
	s_nop 0
; __device__ __forceinline__ void xcd_barrier_complete(unsigned* bar, unsigned x, unsigned& nloc, unsigned& nx) {
;     const unsigned G = gridDim.x * gridDim.y * gridDim.z;
;     unsigned sum, cnt, mine, sp = 0u;
; DI void run_phase(PP p, int ph, LAS unsigned char* lds) {
;     ...
;         {
;             const int nunits = (NTOK / 256) * (FN / 256), G = (int)gridDim.x, nfull = nunits % G;
;             const bool part = (nfull > 0 && nfull < G);
;             if (!part || (int)blockIdx.x >= nfull) {
;                 const int nwk = part ? G - nfull : 0, wk = part ? (int)blockIdx.x - nfull : 0;
;                 if (l == 0) conv_big(p, lds, 0, 1, nwk, wk);
;                 conv_big(p, lds, l, 2, nwk, wk); conv_big(p, lds, l, 3, nwk, wk);
;             }
;         }
	v_writelane_b32 v253, s7, 56
	s_cselect_b32 s6, s5, s4
	s_ashr_i32 s5, s6, 31
	v_writelane_b32 v253, s5, 57
	s_lshr_b32 s5, s5, 29
	s_add_i32 s5, s6, s5
	s_ashr_i32 s7, s5, 3
	v_writelane_b32 v253, s7, 58
	s_and_b32 s5, s5, -8
	v_writelane_b32 v253, s6, 59
	s_sub_i32 s5, s6, s5
	v_writelane_b32 v253, s5, 60
	s_ashr_i32 s5, s12, 31
	v_writelane_b32 v253, s5, 61
	s_lshr_b32 s5, s5, 29
	s_mul_hi_u32 s4, s8, s13
	s_add_i32 s5, s12, s5
	s_mul_i32 s4, s4, s64
	s_ashr_i32 s6, s5, 3
	s_and_b32 s5, s5, -8
	s_sub_i32 s4, s8, s4
	v_writelane_b32 v253, s6, 62
	s_sub_i32 s5, s12, s5
	v_writelane_b32 v253, s5, 63
	s_sub_i32 s5, s4, s64
	s_cmp_ge_u32 s4, s64
	s_cselect_b32 s4, s5, s4
	s_sub_i32 s5, s4, s64
	s_cmp_ge_u32 s4, s64
	s_cselect_b32 s7, s5, s4
	s_abs_i32 s4, s64
	v_cvt_f32_u32_e32 v1, s4
	s_sub_i32 s5, 0, s4
	v_rcp_iflag_f32_e32 v1, v1
	s_nop 0
	v_mul_f32_e32 v1, 0x4f7ffffe, v1
	v_cvt_u32_f32_e32 v1, v1
	s_nop 0
	v_readfirstlane_b32 s6, v1
	s_mul_i32 s5, s5, s6
	s_mul_hi_u32 s5, s6, s5
	s_add_i32 s6, s6, s5
	s_ashr_i32 s5, s7, 31
	v_writelane_b32 v251, s5, 0
	s_lshr_b32 s5, s5, 29
	s_add_i32 s5, s7, s5
	s_ashr_i32 s8, s5, 3
	v_writelane_b32 v251, s8, 1
	s_and_b32 s5, s5, -8
	v_writelane_b32 v251, s7, 2
	s_sub_i32 s5, s7, s5
	v_writelane_b32 v251, s5, 3
	s_ashr_i32 s5, s15, 31
	v_writelane_b32 v251, s5, 4
	s_lshr_b32 s5, s5, 29
	s_add_i32 s5, s15, s5
	s_ashr_i32 s7, s5, 3
	s_and_b32 s5, s5, -8
	v_writelane_b32 v251, s7, 5
	s_sub_i32 s5, s15, s5
	v_writelane_b32 v251, s5, 6
	s_mul_hi_u32 s5, s6, 0x558
	s_mul_i32 s5, s5, s4
	s_sub_i32 s5, 0x558, s5
	s_sub_i32 s6, s5, s4
	s_cmp_ge_u32 s5, s4
	s_cselect_b32 s5, s6, s5
	s_sub_i32 s6, s5, s4
	s_cmp_ge_u32 s5, s4
	s_cselect_b32 s8, s6, s5
	s_cmp_lg_u32 s8, 0
	s_cselect_b64 s[4:5], -1, 0
	s_and_b64 s[0:1], s[0:1], s[4:5]
	s_xor_b64 s[4:5], s[0:1], -1
	s_cmp_ge_i32 s2, s8
	s_cselect_b64 s[6:7], -1, 0
	s_or_b64 s[4:5], s[6:7], s[4:5]
	v_writelane_b32 v251, s4, 7
	s_sub_i32 s6, s64, s8
	v_lshrrev_b32_e32 v1, 20, v0
	v_writelane_b32 v251, s5, 8
	s_and_b64 s[4:5], s[0:1], exec
	s_cselect_b32 s4, s6, 0
	s_sub_i32 s5, s2, s8
	s_and_b64 s[0:1], s[0:1], exec
	s_load_dword s1, s[76:77], 0x120
	s_mul_i32 s0, s65, s64
	s_cselect_b32 s5, s5, 0
	s_cmp_eq_u32 s4, 0
	v_lshrrev_b32_e32 v0, 10, v0
	s_waitcnt lgkmcnt(0)
	s_mul_i32 s0, s0, s1
	v_writelane_b32 v251, s0, 9
	s_cselect_b64 s[0:1], -1, 0
	v_writelane_b32 v251, s0, 10
	v_or_b32_e32 v0, v0, v1
	v_mbcnt_lo_u32_b32 v1, -1, 0
	v_writelane_b32 v251, s1, 11
	s_and_b64 s[0:1], s[0:1], exec
	s_cselect_b32 s7, s23, s5
	s_cselect_b32 s6, s64, s6
	s_cmpk_lt_i32 s7, 0x400
	v_writelane_b32 v251, s5, 12
	s_cselect_b64 s[0:1], -1, 0
	v_writelane_b32 v251, s0, 13
	v_mbcnt_hi_u32_b32 v185, -1, v1
	s_movk_i32 s65, 0x60
	v_writelane_b32 v251, s1, 14
	s_sub_i32 s0, 0xffffb801, s20
	s_max_i32 s0, s3, s0
	s_mul_hi_u32 s1, s0, s22
	s_mul_i32 s4, s1, s21
	s_sub_i32 s0, s0, s4
	s_ashr_i32 s3, s3, 31
	s_xor_b32 s3, s3, s18
	s_add_i32 s4, s1, 1
	s_sub_i32 s5, s0, s21
	s_cmp_ge_u32 s0, s21
	s_cselect_b32 s1, s4, s1
	s_cselect_b32 s0, s5, s0
	s_add_i32 s4, s1, 1
	s_cmp_ge_u32 s0, s21
	v_writelane_b32 v251, s20, 15
	s_cselect_b32 s0, s4, s1
	v_writelane_b32 v251, s22, 16
	s_xor_b32 s0, s0, s3
	v_writelane_b32 v251, s18, 17
	s_sub_i32 s0, s0, s3
	v_writelane_b32 v251, s21, 18
	s_movk_i32 s1, 0x3ff
	s_cmp_gt_i32 s0, 0
	v_and_or_b32 v0, v0, s1, v167
	v_writelane_b32 v251, s0, 19
	s_cselect_b64 s[0:1], -1, 0
	v_writelane_b32 v251, s0, 20
	s_bitcmp1_b32 s2, 0
	s_movk_i32 s21, 0x4b00
	v_writelane_b32 v251, s1, 21
	s_cselect_b64 s[0:1], -1, 0
	v_writelane_b32 v251, s0, 22
	s_bitcmp1_b32 s64, 0
	s_cselect_b64 s[58:59], -1, 0
	v_writelane_b32 v251, s1, 23
	s_lshl_b32 s0, s19, 1
	v_writelane_b32 v251, s0, 24
	v_writelane_b32 v251, s23, 25
	s_lshl_b32 s0, s23, 8
	v_writelane_b32 v251, s0, 26
	v_writelane_b32 v251, s24, 27
	s_lshl_b32 s0, s24, 8
	v_writelane_b32 v251, s0, 28
	v_writelane_b32 v251, s16, 29
	s_lshl_b32 s0, s16, 8
	v_writelane_b32 v251, s0, 30
	v_writelane_b32 v251, s15, 31
	s_lshl_b32 s0, s15, 6
	v_writelane_b32 v251, s0, 32
	v_writelane_b32 v251, s14, 33
	s_lshl_b32 s0, s14, 6
	v_writelane_b32 v251, s0, 34
	v_writelane_b32 v251, s12, 35
	s_lshl_b32 s0, s12, 6
	v_writelane_b32 v251, s0, 36
	v_writelane_b32 v251, s11, 37
	s_lshl_b32 s0, s11, 6
	v_writelane_b32 v251, s0, 38
	v_writelane_b32 v251, s10, 39
	s_lshl_b32 s0, s10, 8
	v_writelane_b32 v251, s0, 40
	v_writelane_b32 v251, s6, 41
	s_lshl_b32 s0, s6, 8
	v_writelane_b32 v251, s0, 42
	v_writelane_b32 v251, s7, 43
	s_lshl_b32 s0, s7, 8
	v_writelane_b32 v251, s0, 44
	s_add_i32 s0, 0, 0xb00
	v_writelane_b32 v251, s0, 45
	s_add_i32 s0, 0, 0x10c00
	v_writelane_b32 v251, s0, 46
	s_add_i32 s0, 0, 0x20004
	v_writelane_b32 v251, s0, 47
	v_cmp_eq_u32_e64 s[0:1], 0, v0
	s_lshl_b32 s17, s64, 8
	s_lshl_b32 s18, s64, 6
	v_writelane_b32 v251, s0, 48
	s_movk_i32 s16, 0x80
	s_movk_i32 s19, 0x180
	v_writelane_b32 v251, s1, 49
	s_mov_b32 s0, s2
	v_writelane_b32 v251, s0, 50
	s_mov_b32 s12, 0x3f317217
	s_mov_b32 s20, 0x7f800000
	v_writelane_b32 v251, s1, 51
	v_writelane_b32 v251, s76, 52
	s_mov_b64 s[14:15], 0x4000
	s_nop 0
	v_writelane_b32 v251, s77, 53
	v_writelane_b32 v251, s78, 54
	v_writelane_b32 v251, s58, 55
	s_nop 1
	v_writelane_b32 v251, s59, 56
	s_branch .LBB0_11
